# HGRN2 matrix-core loop: suffix-scan + swizzle total, scaled state reused for the inter term, previous block's state-update MFMAs deferred under this block's decay scaling
# speedup vs baseline: 1.0080x; 1.0003x over previous
.Lgla_st_join_1:
	v_lshlrev_b32_e32 v184, 16, v120
	v_and_b32_e32 v185, s69, v120
	v_lshlrev_b32_e32 v186, 16, v121
	v_and_b32_e32 v187, s69, v121
	v_lshlrev_b32_e32 v188, 16, v124
	v_and_b32_e32 v189, s69, v124
	ds_write_b128 v139, v[180:183] offset:8192
	ds_write_b128 v139, v[184:187] offset:17408
	ds_write2_b32 v140, v188, v189 offset1:4
	global_load_dwordx2 v[126:127], v130, s[8:9]
	global_load_dwordx2 v[190:191], v130, s[8:9] offset:1024
	global_load_dword v119, v131, s[8:9]
	s_add_u32 s8, s8, 0x34000
	s_addc_u32 s9, s9, 0
	global_load_dword v152, v131, s[8:9]
	global_load_dword v152, v131, s[8:9]
	global_load_dwordx2 v[120:121], v130, s[8:9]
	global_load_dwordx2 v[122:123], v130, s[8:9] offset:1024
	global_load_dword v124, v131, s[8:9]
	s_add_u32 s8, s8, 0x34000
	s_addc_u32 s9, s9, 0
	global_load_dword v152, v131, s[8:9]
	global_load_dword v152, v131, s[8:9]
	s_waitcnt lgkmcnt(0)
	s_barrier
	s_cmp_eq_u32 s14, 0
	s_cbranch_scc1 .Lgla_ret_setup
	v_mov_b32_e32 v96, 0
	v_mov_b32_e32 v97, 0
	v_mov_b32_e32 v98, 0
	v_mov_b32_e32 v99, 0
	v_mov_b32_e32 v100, 0
	v_mov_b32_e32 v101, 0
	v_mov_b32_e32 v102, 0
	v_mov_b32_e32 v103, 0
	v_mov_b32_e32 v40, 0
	v_mov_b32_e32 v41, 0
	v_mov_b32_e32 v42, 0
	v_mov_b32_e32 v43, 0
	v_and_b32_e32 v154, 15, v163
	v_bfe_u32 v155, v163, 4, 2
	v_lshrrev_b32_e32 v156, 6, v163
	v_mul_u32_u24_e32 v56, 528, v154
	v_lshl_add_u32 v56, v156, 6, v56
	v_lshl_add_u32 v56, v155, 4, v56
	v_mul_u32_u24_e32 v57, 528, v155
	v_lshl_add_u32 v57, v156, 6, v57
	v_lshl_add_u32 v57, v154, 2, v57
	v_lshrrev_b32_e32 v158, 1, v155
	v_and_b32_e32 v159, 1, v155
	v_lshlrev_b32_e32 v58, 8, v158
	v_lshl_add_u32 v58, v154, 4, v58
	v_lshl_add_u32 v58, v159, 3, v58
	v_mul_u32_u24_e32 v158, 1040, v154
	v_lshl_add_u32 v158, v156, 7, v158
	v_lshl_add_u32 v158, v155, 4, v158
	v_add_u32_e32 v59, 0x10000, v158
	v_add_u32_e32 v60, 0x14400, v158
	v_mul_u32_u24_e32 v158, 1280, v156
	v_add_u32_e32 v158, 0x19000, v158
	v_mul_u32_u24_e32 v61, 80, v154
	v_add_u32_e32 v61, v61, v158
	v_lshl_add_u32 v61, v155, 4, v61
	v_mul_u32_u24_e32 v62, 80, v155
	v_add_u32_e32 v62, v62, v158
	v_lshl_add_u32 v62, v154, 2, v62
	v_lshl_add_u32 v161, v155, 2, 0
	v_cmp_le_u32_e32 vcc, v161, v154
	s_nop 1
	v_cndmask_b32_e64 v48, 0, 1.0, vcc
	v_lshl_add_u32 v161, v155, 2, 1
	v_cmp_le_u32_e32 vcc, v161, v154
	s_nop 1
	v_cndmask_b32_e64 v49, 0, 1.0, vcc
	v_lshl_add_u32 v161, v155, 2, 2
	v_cmp_le_u32_e32 vcc, v161, v154
	s_nop 1
	v_cndmask_b32_e64 v50, 0, 1.0, vcc
	v_lshl_add_u32 v161, v155, 2, 3
	v_cmp_le_u32_e32 vcc, v161, v154
	s_nop 1
	v_cndmask_b32_e64 v51, 0, 1.0, vcc
	.p2align 6
.Lgla_loop_hgrn:
	ds_read_b128 v[20:23], v56 offset:17408
	ds_read_b128 v[24:27], v56 offset:8192
	ds_read_b64 v[32:33], v58 offset:26624
	ds_read_b64 v[34:35], v58 offset:27136
	ds_read_b64 v[36:37], v58 offset:27648
	ds_read_b64 v[38:39], v58 offset:28160
	ds_read2_b32 v[104:105], v150 offset0:0 offset1:32
	ds_read2_b32 v[106:107], v150 offset0:64 offset1:96
	ds_read2_b32 v[108:109], v150 offset0:128 offset1:160
	ds_read2_b32 v[110:111], v150 offset0:192 offset1:224
	s_waitcnt lgkmcnt(8)
	v_mfma_f32_16x16x4_f32 v[0:3], v40, v96, v[0:3]
	v_add_f32_dpp v72, v24, v24 row_shl:1 row_mask:0xf bank_mask:0xf bound_ctrl:0
	v_add_f32_dpp v73, v25, v25 row_shl:1 row_mask:0xf bank_mask:0xf bound_ctrl:0
	v_add_f32_dpp v74, v26, v26 row_shl:1 row_mask:0xf bank_mask:0xf bound_ctrl:0
	v_add_f32_dpp v75, v27, v27 row_shl:1 row_mask:0xf bank_mask:0xf bound_ctrl:0
	v_add_f32_dpp v72, v72, v72 row_shl:2 row_mask:0xf bank_mask:0xf bound_ctrl:0
	v_add_f32_dpp v73, v73, v73 row_shl:2 row_mask:0xf bank_mask:0xf bound_ctrl:0
	v_mfma_f32_16x16x4_f32 v[4:7], v40, v97, v[4:7]
	v_add_f32_dpp v74, v74, v74 row_shl:2 row_mask:0xf bank_mask:0xf bound_ctrl:0
	v_add_f32_dpp v75, v75, v75 row_shl:2 row_mask:0xf bank_mask:0xf bound_ctrl:0
	v_add_f32_dpp v72, v72, v72 row_shl:4 row_mask:0xf bank_mask:0xf bound_ctrl:0
	v_add_f32_dpp v73, v73, v73 row_shl:4 row_mask:0xf bank_mask:0xf bound_ctrl:0
	v_add_f32_dpp v74, v74, v74 row_shl:4 row_mask:0xf bank_mask:0xf bound_ctrl:0
	v_add_f32_dpp v75, v75, v75 row_shl:4 row_mask:0xf bank_mask:0xf bound_ctrl:0
	v_mfma_f32_16x16x4_f32 v[0:3], v41, v98, v[0:3]
	v_add_f32_dpp v72, v72, v72 row_shl:8 row_mask:0xf bank_mask:0xf bound_ctrl:0
	v_add_f32_dpp v73, v73, v73 row_shl:8 row_mask:0xf bank_mask:0xf bound_ctrl:0
	v_add_f32_dpp v74, v74, v74 row_shl:8 row_mask:0xf bank_mask:0xf bound_ctrl:0
	v_add_f32_dpp v75, v75, v75 row_shl:8 row_mask:0xf bank_mask:0xf bound_ctrl:0
	v_exp_f32_e32 v76, v24
	v_exp_f32_e32 v77, v25
	v_mfma_f32_16x16x4_f32 v[4:7], v41, v99, v[4:7]
	v_exp_f32_e32 v78, v26
	v_exp_f32_e32 v79, v27
	ds_swizzle_b32 v92, v72 offset:swizzle(BITMASK_PERM,"p0000")
	ds_swizzle_b32 v93, v73 offset:swizzle(BITMASK_PERM,"p0000")
	ds_swizzle_b32 v94, v74 offset:swizzle(BITMASK_PERM,"p0000")
	ds_swizzle_b32 v95, v75 offset:swizzle(BITMASK_PERM,"p0000")
	v_mfma_f32_16x16x4_f32 v[0:3], v42, v100, v[0:3]
	v_sub_f32_e32 v80, v72, v24
	v_sub_f32_e32 v81, v73, v25
	v_sub_f32_e32 v82, v74, v26
	v_sub_f32_e32 v83, v75, v27
	v_max_f32_e32 v80, 0xc2fc0000, v80
	v_max_f32_e32 v81, 0xc2fc0000, v81
	v_mfma_f32_16x16x4_f32 v[4:7], v42, v101, v[4:7]
	v_max_f32_e32 v82, 0xc2fc0000, v82
	v_max_f32_e32 v83, 0xc2fc0000, v83
	v_sub_f32_e32 v76, 1.0, v76
	v_sub_f32_e32 v77, 1.0, v77
	v_sub_f32_e32 v78, 1.0, v78
	v_sub_f32_e32 v79, 1.0, v79
	v_mfma_f32_16x16x4_f32 v[0:3], v43, v102, v[0:3]
	v_exp_f32_e64 v84, -v80
	v_exp_f32_e64 v85, -v81
	v_exp_f32_e64 v86, -v82
	v_exp_f32_e64 v87, -v83
	v_exp_f32_e32 v80, v80
	v_exp_f32_e32 v81, v81
	v_mfma_f32_16x16x4_f32 v[4:7], v43, v103, v[4:7]
	v_exp_f32_e32 v82, v82
	v_exp_f32_e32 v83, v83
	s_waitcnt lgkmcnt(0)
	v_exp_f32_e32 v88, v92
	v_exp_f32_e32 v89, v93
	v_exp_f32_e32 v90, v94
	v_exp_f32_e32 v91, v95
	v_mul_f32_e32 v24, v76, v80
	v_mul_f32_e32 v25, v77, v81
	v_mul_f32_e32 v26, v78, v82
	v_mul_f32_e32 v27, v79, v83
	v_mul_f32_e32 v20, v20, v84
	v_mul_f32_e32 v21, v21, v85
	v_mul_f32_e32 v22, v22, v86
	v_mul_f32_e32 v23, v23, v87
	s_nop 3
	v_pk_mul_f32 v[0:1], v[0:1], v[88:89]
	v_pk_mul_f32 v[2:3], v[2:3], v[90:91]
	v_pk_mul_f32 v[4:5], v[4:5], v[88:89]
	v_pk_mul_f32 v[6:7], v[6:7], v[90:91]
	ds_write_b128 v61, v[24:27]
	ds_read_b32 v28, v62 offset:0
	ds_read_b32 v29, v62 offset:320
	ds_read_b32 v30, v62 offset:640
	ds_read_b32 v31, v62 offset:960
	v_mfma_f32_16x16x4_f32 v[16:19], v24, v20, 0
	s_waitcnt vmcnt(7)
	v_lshlrev_b32_e32 v180, 16, v190
	v_and_b32_e32 v181, s69, v190
	v_lshlrev_b32_e32 v182, 16, v191
	v_mfma_f32_16x16x4_f32 v[8:11], v0, v20, 0
	v_and_b32_e32 v183, s69, v191
	v_lshlrev_b32_e32 v184, 16, v126
	v_and_b32_e32 v185, s69, v126
	v_lshlrev_b32_e32 v186, 16, v127
	v_mfma_f32_16x16x4_f32 v[16:19], v25, v21, v[16:19]
	v_and_b32_e32 v187, s69, v127
	v_lshlrev_b32_e32 v188, 16, v119
	v_and_b32_e32 v189, s69, v119
	v_mul_f32_e32 v180, 0x3fb8aa3b, v180
	v_mfma_f32_16x16x4_f32 v[12:15], v4, v20, 0
	v_mul_f32_e32 v181, 0x3fb8aa3b, v181
	v_mul_f32_e32 v182, 0x3fb8aa3b, v182
	v_mul_f32_e32 v183, 0x3fb8aa3b, v183
	ds_write_b128 v139, v[180:183] offset:40960
	v_mfma_f32_16x16x4_f32 v[16:19], v26, v22, v[16:19]
	ds_write_b128 v139, v[184:187] offset:50176
	ds_write2_b32 v153, v188, v189 offset1:4
	global_load_dwordx2 v[126:127], v130, s[8:9]
	global_load_dwordx2 v[190:191], v130, s[8:9] offset:1024
	v_mfma_f32_16x16x4_f32 v[8:11], v1, v21, v[8:11]
	global_load_dword v119, v131, s[8:9]
	s_add_u32 s8, s8, 0x34000
	s_addc_u32 s9, s9, 0
	s_waitcnt lgkmcnt(12)
	v_add_f32_e32 v112, v104, v105
	v_add_f32_e32 v112, v112, v106
	v_mfma_f32_16x16x4_f32 v[16:19], v27, v23, v[16:19]
	v_add_f32_e32 v112, v112, v107
	v_add_f32_e32 v112, v112, v108
	v_add_f32_e32 v112, v112, v109
	v_add_f32_e32 v112, v112, v110
	v_mfma_f32_16x16x4_f32 v[12:15], v5, v21, v[12:15]
	v_add_f32_e32 v112, v112, v111
	v_mul_f32_e32 v113, v112, v112
	v_cvt_pk_bf16_f32 v116, v112, v129
	v_mov_b32_e32 v117, v112
	v_mfma_f32_16x16x4_f32 v[8:11], v2, v22, v[8:11]
	v_mov_b32_e32 v118, v113
	global_store_short v132, v116, s[10:11]
	s_nop 1
	v_permlane16_swap_b32_e32 v112, v117
	v_permlane16_swap_b32_e32 v113, v118
	v_mfma_f32_16x16x4_f32 v[12:15], v6, v22, v[12:15]
	v_add_f32_e32 v112, v112, v117
	v_add_f32_e32 v113, v113, v118
	s_nop 1
	v_add_f32_dpp v112, v112, v112 row_ror:8 row_mask:0xf bank_mask:0xf
	v_add_f32_dpp v113, v113, v113 row_ror:8 row_mask:0xf bank_mask:0xf
	v_mfma_f32_16x16x4_f32 v[8:11], v3, v23, v[8:11]
	s_nop 1
	v_add_f32_dpp v112, v112, v112 row_ror:4 row_mask:0xf bank_mask:0xf
	v_add_f32_dpp v113, v113, v113 row_ror:4 row_mask:0xf bank_mask:0xf
	s_nop 1
	v_add_f32_dpp v112, v112, v112 row_ror:2 row_mask:0xf bank_mask:0xf
	v_add_f32_dpp v113, v113, v113 row_ror:2 row_mask:0xf bank_mask:0xf
	v_mfma_f32_16x16x4_f32 v[12:15], v7, v23, v[12:15]
	s_nop 1
	v_add_f32_dpp v112, v112, v112 row_ror:1 row_mask:0xf bank_mask:0xf
	v_add_f32_dpp v113, v113, v113 row_ror:1 row_mask:0xf bank_mask:0xf
	v_mov_b32_e32 v114, 0
	v_mov_b32_e32 v115, 0
	s_waitcnt lgkmcnt(3)
	v_pk_mul_f32 v[16:17], v[16:17], v[48:49]
	v_pk_mul_f32 v[18:19], v[18:19], v[50:51]
	s_nop 1
	v_permlane16_swap_b32_e32 v16, v17
	v_permlane16_swap_b32_e32 v18, v19
	s_nop 1
	v_permlane32_swap_b32_e32 v16, v18
	v_permlane32_swap_b32_e32 v17, v19
	s_nop 1
	v_mfma_f32_16x16x4_f32 v[8:11], v32, v16, v[8:11]
	s_nop 0
	s_mov_b64 exec, s[18:19]
	global_store_dwordx4 v133, v[112:115], s[12:13]
	s_mov_b64 exec, -1
	s_cmp_eq_u32 s15, 512
	s_cselect_b32 s20, 0, 0x10000
	s_cselect_b32 s21, 0, 0x1000
	s_add_u32 s10, s10, s20
	s_addc_u32 s11, s11, 0
	s_add_u32 s12, s12, s21
	s_addc_u32 s13, s13, 0
	v_mfma_f32_16x16x4_f32 v[12:15], v33, v16, v[12:15]
	v_mfma_f32_16x16x4_f32 v[8:11], v34, v17, v[8:11]
	v_mfma_f32_16x16x4_f32 v[12:15], v35, v17, v[12:15]
	v_mfma_f32_16x16x4_f32 v[8:11], v36, v18, v[8:11]
	v_mfma_f32_16x16x4_f32 v[12:15], v37, v18, v[12:15]
	v_mfma_f32_16x16x4_f32 v[8:11], v38, v19, v[8:11]
	v_mfma_f32_16x16x4_f32 v[12:15], v39, v19, v[12:15]
	s_nop 7
	s_nop 1
	ds_write_b128 v59, v[8:11]
	ds_write_b128 v59, v[12:15] offset:64
	s_sub_u32 s15, s15, 1
	s_waitcnt lgkmcnt(0)
	s_barrier
	ds_read_b128 v[20:23], v56 offset:50176
	ds_read_b128 v[24:27], v56 offset:40960
	ds_read_b64 v[96:97], v58 offset:59392
	ds_read_b64 v[98:99], v58 offset:59904
	ds_read_b64 v[100:101], v58 offset:60416
	ds_read_b64 v[102:103], v58 offset:60928
	ds_read2_b32 v[104:105], v149 offset0:0 offset1:32
	ds_read2_b32 v[106:107], v149 offset0:64 offset1:96
	ds_read2_b32 v[108:109], v149 offset0:128 offset1:160
	ds_read2_b32 v[110:111], v149 offset0:192 offset1:224
	s_waitcnt lgkmcnt(8)
	v_mfma_f32_16x16x4_f32 v[0:3], v28, v32, v[0:3]
	v_add_f32_dpp v72, v24, v24 row_shl:1 row_mask:0xf bank_mask:0xf bound_ctrl:0
	v_add_f32_dpp v73, v25, v25 row_shl:1 row_mask:0xf bank_mask:0xf bound_ctrl:0
	v_add_f32_dpp v74, v26, v26 row_shl:1 row_mask:0xf bank_mask:0xf bound_ctrl:0
	v_add_f32_dpp v75, v27, v27 row_shl:1 row_mask:0xf bank_mask:0xf bound_ctrl:0
	v_add_f32_dpp v72, v72, v72 row_shl:2 row_mask:0xf bank_mask:0xf bound_ctrl:0
	v_add_f32_dpp v73, v73, v73 row_shl:2 row_mask:0xf bank_mask:0xf bound_ctrl:0
	v_mfma_f32_16x16x4_f32 v[4:7], v28, v33, v[4:7]
	v_add_f32_dpp v74, v74, v74 row_shl:2 row_mask:0xf bank_mask:0xf bound_ctrl:0
	v_add_f32_dpp v75, v75, v75 row_shl:2 row_mask:0xf bank_mask:0xf bound_ctrl:0
	v_add_f32_dpp v72, v72, v72 row_shl:4 row_mask:0xf bank_mask:0xf bound_ctrl:0
	v_add_f32_dpp v73, v73, v73 row_shl:4 row_mask:0xf bank_mask:0xf bound_ctrl:0
	v_add_f32_dpp v74, v74, v74 row_shl:4 row_mask:0xf bank_mask:0xf bound_ctrl:0
	v_add_f32_dpp v75, v75, v75 row_shl:4 row_mask:0xf bank_mask:0xf bound_ctrl:0
	v_mfma_f32_16x16x4_f32 v[0:3], v29, v34, v[0:3]
	v_add_f32_dpp v72, v72, v72 row_shl:8 row_mask:0xf bank_mask:0xf bound_ctrl:0
	v_add_f32_dpp v73, v73, v73 row_shl:8 row_mask:0xf bank_mask:0xf bound_ctrl:0
	v_add_f32_dpp v74, v74, v74 row_shl:8 row_mask:0xf bank_mask:0xf bound_ctrl:0
	v_add_f32_dpp v75, v75, v75 row_shl:8 row_mask:0xf bank_mask:0xf bound_ctrl:0
	v_exp_f32_e32 v76, v24
	v_exp_f32_e32 v77, v25
	v_mfma_f32_16x16x4_f32 v[4:7], v29, v35, v[4:7]
	v_exp_f32_e32 v78, v26
	v_exp_f32_e32 v79, v27
	ds_swizzle_b32 v92, v72 offset:swizzle(BITMASK_PERM,"p0000")
	ds_swizzle_b32 v93, v73 offset:swizzle(BITMASK_PERM,"p0000")
	ds_swizzle_b32 v94, v74 offset:swizzle(BITMASK_PERM,"p0000")
	ds_swizzle_b32 v95, v75 offset:swizzle(BITMASK_PERM,"p0000")
	v_mfma_f32_16x16x4_f32 v[0:3], v30, v36, v[0:3]
	v_sub_f32_e32 v80, v72, v24
	v_sub_f32_e32 v81, v73, v25
	v_sub_f32_e32 v82, v74, v26
	v_sub_f32_e32 v83, v75, v27
	v_max_f32_e32 v80, 0xc2fc0000, v80
	v_max_f32_e32 v81, 0xc2fc0000, v81
	v_mfma_f32_16x16x4_f32 v[4:7], v30, v37, v[4:7]
	v_max_f32_e32 v82, 0xc2fc0000, v82
	v_max_f32_e32 v83, 0xc2fc0000, v83
	v_sub_f32_e32 v76, 1.0, v76
	v_sub_f32_e32 v77, 1.0, v77
	v_sub_f32_e32 v78, 1.0, v78
	v_sub_f32_e32 v79, 1.0, v79
	v_mfma_f32_16x16x4_f32 v[0:3], v31, v38, v[0:3]
	v_exp_f32_e64 v84, -v80
	v_exp_f32_e64 v85, -v81
	v_exp_f32_e64 v86, -v82
	v_exp_f32_e64 v87, -v83
	v_exp_f32_e32 v80, v80
	v_exp_f32_e32 v81, v81
	v_mfma_f32_16x16x4_f32 v[4:7], v31, v39, v[4:7]
	v_exp_f32_e32 v82, v82
	v_exp_f32_e32 v83, v83
	s_waitcnt lgkmcnt(0)
	v_exp_f32_e32 v88, v92
	v_exp_f32_e32 v89, v93
	v_exp_f32_e32 v90, v94
	v_exp_f32_e32 v91, v95
	v_mul_f32_e32 v24, v76, v80
	v_mul_f32_e32 v25, v77, v81
	v_mul_f32_e32 v26, v78, v82
	v_mul_f32_e32 v27, v79, v83
	v_mul_f32_e32 v20, v20, v84
	v_mul_f32_e32 v21, v21, v85
	v_mul_f32_e32 v22, v22, v86
	v_mul_f32_e32 v23, v23, v87
	s_nop 3
	v_pk_mul_f32 v[0:1], v[0:1], v[88:89]
	v_pk_mul_f32 v[2:3], v[2:3], v[90:91]
	v_pk_mul_f32 v[4:5], v[4:5], v[88:89]
	v_pk_mul_f32 v[6:7], v[6:7], v[90:91]
	ds_write_b128 v61, v[24:27]
	ds_read_b32 v40, v62 offset:0
	ds_read_b32 v41, v62 offset:320
	ds_read_b32 v42, v62 offset:640
	ds_read_b32 v43, v62 offset:960
	v_mfma_f32_16x16x4_f32 v[16:19], v24, v20, 0
	s_waitcnt vmcnt(7)
	v_lshlrev_b32_e32 v180, 16, v122
	v_and_b32_e32 v181, s69, v122
	v_lshlrev_b32_e32 v182, 16, v123
	v_mfma_f32_16x16x4_f32 v[8:11], v0, v20, 0
	v_and_b32_e32 v183, s69, v123
	v_lshlrev_b32_e32 v184, 16, v120
	v_and_b32_e32 v185, s69, v120
	v_lshlrev_b32_e32 v186, 16, v121
	v_mfma_f32_16x16x4_f32 v[16:19], v25, v21, v[16:19]
	v_and_b32_e32 v187, s69, v121
	v_lshlrev_b32_e32 v188, 16, v124
	v_and_b32_e32 v189, s69, v124
	v_mul_f32_e32 v180, 0x3fb8aa3b, v180
	v_mfma_f32_16x16x4_f32 v[12:15], v4, v20, 0
	v_mul_f32_e32 v181, 0x3fb8aa3b, v181
	v_mul_f32_e32 v182, 0x3fb8aa3b, v182
	v_mul_f32_e32 v183, 0x3fb8aa3b, v183
	ds_write_b128 v139, v[180:183] offset:8192
	v_mfma_f32_16x16x4_f32 v[16:19], v26, v22, v[16:19]
	ds_write_b128 v139, v[184:187] offset:17408
	ds_write2_b32 v140, v188, v189 offset1:4
	global_load_dwordx2 v[120:121], v130, s[8:9]
	global_load_dwordx2 v[122:123], v130, s[8:9] offset:1024
	v_mfma_f32_16x16x4_f32 v[8:11], v1, v21, v[8:11]
	global_load_dword v124, v131, s[8:9]
	s_add_u32 s8, s8, 0x34000
	s_addc_u32 s9, s9, 0
	s_waitcnt lgkmcnt(12)
	v_add_f32_e32 v112, v104, v105
	v_add_f32_e32 v112, v112, v106
	v_mfma_f32_16x16x4_f32 v[16:19], v27, v23, v[16:19]
	v_add_f32_e32 v112, v112, v107
	v_add_f32_e32 v112, v112, v108
	v_add_f32_e32 v112, v112, v109
	v_add_f32_e32 v112, v112, v110
	v_mfma_f32_16x16x4_f32 v[12:15], v5, v21, v[12:15]
	v_add_f32_e32 v112, v112, v111
	v_mul_f32_e32 v113, v112, v112
	v_cvt_pk_bf16_f32 v116, v112, v129
	v_mov_b32_e32 v117, v112
	v_mfma_f32_16x16x4_f32 v[8:11], v2, v22, v[8:11]
	v_mov_b32_e32 v118, v113
	global_store_short v132, v116, s[10:11]
	s_nop 1
	v_permlane16_swap_b32_e32 v112, v117
	v_permlane16_swap_b32_e32 v113, v118
	v_mfma_f32_16x16x4_f32 v[12:15], v6, v22, v[12:15]
	v_add_f32_e32 v112, v112, v117
	v_add_f32_e32 v113, v113, v118
	s_nop 1
	v_add_f32_dpp v112, v112, v112 row_ror:8 row_mask:0xf bank_mask:0xf
	v_add_f32_dpp v113, v113, v113 row_ror:8 row_mask:0xf bank_mask:0xf
	v_mfma_f32_16x16x4_f32 v[8:11], v3, v23, v[8:11]
	s_nop 1
	v_add_f32_dpp v112, v112, v112 row_ror:4 row_mask:0xf bank_mask:0xf
	v_add_f32_dpp v113, v113, v113 row_ror:4 row_mask:0xf bank_mask:0xf
	s_nop 1
	v_add_f32_dpp v112, v112, v112 row_ror:2 row_mask:0xf bank_mask:0xf
	v_add_f32_dpp v113, v113, v113 row_ror:2 row_mask:0xf bank_mask:0xf
	v_mfma_f32_16x16x4_f32 v[12:15], v7, v23, v[12:15]
	s_nop 1
	v_add_f32_dpp v112, v112, v112 row_ror:1 row_mask:0xf bank_mask:0xf
	v_add_f32_dpp v113, v113, v113 row_ror:1 row_mask:0xf bank_mask:0xf
	v_mov_b32_e32 v114, 0
	v_mov_b32_e32 v115, 0
	s_waitcnt lgkmcnt(3)
	v_pk_mul_f32 v[16:17], v[16:17], v[48:49]
	v_pk_mul_f32 v[18:19], v[18:19], v[50:51]
	s_nop 1
	v_permlane16_swap_b32_e32 v16, v17
	v_permlane16_swap_b32_e32 v18, v19
	s_nop 1
	v_permlane32_swap_b32_e32 v16, v18
	v_permlane32_swap_b32_e32 v17, v19
	s_nop 1
	v_mfma_f32_16x16x4_f32 v[8:11], v96, v16, v[8:11]
	s_nop 0
	s_mov_b64 exec, s[18:19]
	global_store_dwordx4 v133, v[112:115], s[12:13]
	s_mov_b64 exec, -1
	s_cmp_eq_u32 s15, 512
	s_cselect_b32 s20, 0, 0x10000
	s_cselect_b32 s21, 0, 0x1000
	s_add_u32 s10, s10, s20
	s_addc_u32 s11, s11, 0
	s_add_u32 s12, s12, s21
	s_addc_u32 s13, s13, 0
	v_mfma_f32_16x16x4_f32 v[12:15], v97, v16, v[12:15]
	v_mfma_f32_16x16x4_f32 v[8:11], v98, v17, v[8:11]
	v_mfma_f32_16x16x4_f32 v[12:15], v99, v17, v[12:15]
	v_mfma_f32_16x16x4_f32 v[8:11], v100, v18, v[8:11]
	v_mfma_f32_16x16x4_f32 v[12:15], v101, v18, v[12:15]
	v_mfma_f32_16x16x4_f32 v[8:11], v102, v19, v[8:11]
	v_mfma_f32_16x16x4_f32 v[12:15], v103, v19, v[12:15]
	s_nop 7
	s_nop 1
	ds_write_b128 v60, v[8:11]
	ds_write_b128 v60, v[12:15] offset:64
	s_sub_u32 s15, s15, 1
	s_waitcnt lgkmcnt(0)
	s_barrier
	s_cmp_lg_u32 s15, 0
	s_cbranch_scc1 .Lgla_loop_hgrn
	s_branch .Lgla_tail
